# RWKV chunk prefetch: saddr-form loads (32-bit lane offsets + scalar base), no 64-bit vector address adds
# speedup vs baseline: 1.0133x; 1.0005x over previous
.LBB0_421:
	s_or_b64 exec, exec, s[18:19]
	s_mul_i32 s52, s36, 0x20800
	s_xor_b64 s[76:77], s[22:23], -1
	s_lshl_b64 s[18:19], s[52:53], 2
	s_add_u32 s18, s20, s18
	v_mov_b32_e32 v6, 0xc200
	v_mov_b32_e32 v7, 0xb000
	s_addc_u32 s19, s21, s19
	v_cndmask_b32_e64 v6, v6, v7, s[16:17]
	s_lshl_b32 s16, s34, 1
	s_add_u32 s20, s20, s16
	s_addc_u32 s21, s21, 0
	s_lshl_b32 s22, s35, 2
	s_add_u32 s18, s18, s22
	s_addc_u32 s19, s19, 0
	s_add_u32 s78, s18, 0x118000
	v_readlane_b32 s18, v255, 3
	v_lshlrev_b32_e32 v4, 1, v116
	s_addc_u32 s79, s19, 0
	v_lshl_add_u32 v61, v235, 2, s18
	s_lshl_b32 s18, s37, 1
	v_and_b32_e32 v5, 14, v4
	v_lshrrev_b32_e32 v7, 2, v116
	s_add_u32 s18, s20, s18
	v_and_b32_e32 v52, 16, v7
	s_addc_u32 s19, s21, 0
	v_lshlrev_b32_e32 v16, 1, v5
	v_ashrrev_i32_e32 v87, 4, v116
	v_add_u32_e32 v64, 0, v4
	v_lshlrev_b32_e32 v67, 5, v5
	v_lshl_add_u64 v[4:5], s[18:19], 0, v[16:17]
	v_lshlrev_b32_e32 v16, 8, v52
	v_lshl_or_b32 v69, v139, 10, v16
	v_lshl_or_b32 v16, v87, 8, v122
	v_add_u32_e32 v92, 16, v87
	v_and_b32_e32 v60, 1, v116
	v_add_u32_e32 v91, 0, v16
	v_lshl_or_b32 v16, v92, 8, v122
	v_add_u32_e32 v93, 0, v16
	v_add_u32_e32 v16, 0x11200, v64
	v_cmp_eq_u32_e32 vcc, 0, v60
	v_or_b32_e32 v7, v52, v140
	v_mul_u32_u24_e32 v7, 0x90, v7
	v_cndmask_b32_e32 v98, v61, v16, vcc
	v_add_u32_e32 v16, 0x11000, v64
	v_cndmask_b32_e32 v99, v61, v16, vcc
	v_add_u32_e32 v16, 0x10e00, v64
	v_cndmask_b32_e32 v100, v61, v16, vcc
	v_add_u32_e32 v16, 0x10c00, v64
	v_cndmask_b32_e32 v101, v61, v16, vcc
	v_add_u32_e32 v16, 0x10a00, v64
	s_mov_b64 s[18:19], 0xe488000
	v_cndmask_b32_e32 v102, v61, v16, vcc
	v_add_u32_e32 v16, 0x10800, v64
	v_add3_u32 v62, 0, v6, v7
	v_or_b32_e32 v6, s38, v140
	v_lshl_add_u64 v[18:19], v[4:5], 0, s[18:19]
	s_mov_b32 s18, 0x5040100
	s_movk_i32 s20, 0xffde
	v_add_u32_e32 v97, v106, v105
	v_cndmask_b32_e32 v103, v61, v16, vcc
	v_add_u32_e32 v16, 0x10600, v64
	v_cmp_eq_u32_e64 s[16:17], 0, v6
	v_perm_b32 v7, v153, v151, s18
	v_perm_b32 v6, v149, v147, s18
	v_perm_b32 v5, v145, v143, s18
	v_perm_b32 v4, v142, v141, s18
	v_perm_b32 v11, v165, v163, s18
	v_perm_b32 v10, v162, v161, s18
	v_perm_b32 v9, v160, v159, s18
	v_perm_b32 v8, v158, v157, s18
	v_perm_b32 v15, v186, v184, s18
	v_perm_b32 v14, v182, v180, s18
	v_perm_b32 v13, v178, v176, s18
	v_perm_b32 v12, v174, v173, s18
	v_perm_b32 v27, v198, v195, s18
	v_perm_b32 v26, v194, v193, s18
	v_perm_b32 v25, v192, v191, s18
	v_perm_b32 v24, v190, v189, s18
	v_perm_b32 v35, v156, v155, s18
	v_perm_b32 v34, v154, v152, s18
	v_perm_b32 v33, v150, v148, s18
	v_perm_b32 v32, v146, v144, s18
	v_perm_b32 v39, v172, v171, s18
	v_perm_b32 v38, v170, v169, s18
	v_perm_b32 v37, v168, v167, s18
	v_perm_b32 v36, v166, v164, s18
	v_perm_b32 v43, v188, v187, s18
	v_perm_b32 v42, v185, v183, s18
	v_perm_b32 v41, v181, v179, s18
	v_perm_b32 v40, v177, v175, s18
	v_perm_b32 v47, v204, v203, s18
	v_perm_b32 v46, v202, v201, s18
	v_perm_b32 v45, v200, v199, s18
	v_perm_b32 v44, v197, v196, s18
	v_mad_u64_u32 v[58:59], s[18:19], v97, s20, v[104:105]
	v_cndmask_b32_e32 v104, v61, v16, vcc
	v_add_u32_e32 v16, 0x10400, v64
	v_cndmask_b32_e32 v105, v61, v16, vcc
	v_add_u32_e32 v16, 0x10200, v64
	v_cndmask_b32_e32 v106, v61, v16, vcc
	v_add_u32_e32 v16, 0x10000, v64
	v_cndmask_b32_e32 v107, v61, v16, vcc
	v_add_u32_e32 v16, 0xfe00, v64
	v_cndmask_b32_e32 v108, v61, v16, vcc
	v_add_u32_e32 v16, 0xfc00, v64
	v_cndmask_b32_e32 v109, v61, v16, vcc
	v_add_u32_e32 v16, 0xfa00, v64
	v_cndmask_b32_e32 v110, v61, v16, vcc
	v_add_u32_e32 v16, 0xf800, v64
	v_cndmask_b32_e32 v111, v61, v16, vcc
	v_add_u32_e32 v16, 0xf600, v64
	v_cndmask_b32_e32 v112, v61, v16, vcc
	v_add_u32_e32 v16, 0xf400, v64
	v_cndmask_b32_e32 v113, v61, v16, vcc
	v_add_u32_e32 v16, 0xf200, v64
	v_cndmask_b32_e32 v114, v61, v16, vcc
	v_add_u32_e32 v16, 0xf000, v64
	v_add_u32_e32 v94, v206, v205
	v_cndmask_b32_e32 v115, v61, v16, vcc
	v_add_u32_e32 v16, 0xee00, v64
	v_and_b32_e32 v63, 48, v116
	v_ashrrev_i32_e32 v90, 3, v116
	v_mad_u64_u32 v[52:53], s[18:19], v94, s20, v[116:117]
	v_cndmask_b32_e32 v116, v61, v16, vcc
	v_add_u32_e32 v16, 0xec00, v64
	v_add_u32_e32 v95, v234, v233
	v_cndmask_b32_e32 v122, v61, v16, vcc
	v_add_u32_e32 v16, 0xea00, v64
	v_mad_u64_u32 v[54:55], s[18:19], v95, s20, v[124:125]
	v_add_u32_e32 v96, v237, v236
	v_cndmask_b32_e32 v124, v61, v16, vcc
	v_add_u32_e32 v16, 0xe800, v64
	v_mad_u64_u32 v[56:57], s[18:19], v96, s20, v[126:127]
	v_cndmask_b32_e32 v126, v61, v16, vcc
	v_add_u32_e32 v16, 0xe600, v64
	v_lshl_add_u32 v88, v140, 4, 0
	v_cndmask_b32_e32 v139, v61, v16, vcc
	v_add_u32_e32 v16, 0xe400, v64
	v_mad_i32_i24 v68, v140, -12, v88
	v_cndmask_b32_e32 v140, v61, v16, vcc
	v_add_u32_e32 v16, 0xe200, v64
	v_cndmask_b32_e32 v141, v61, v16, vcc
	v_add_u32_e32 v16, 0xe000, v64
	v_cndmask_b32_e32 v142, v61, v16, vcc
	v_add_u32_e32 v16, 0xde00, v64
	v_cndmask_b32_e32 v143, v61, v16, vcc
	v_add_u32_e32 v16, 0xdc00, v64
	v_cndmask_b32_e32 v144, v61, v16, vcc
	v_add_u32_e32 v16, 0xda00, v64
	v_cndmask_b32_e32 v145, v61, v16, vcc
	v_add_u32_e32 v16, 0xd800, v64
	v_cndmask_b32_e32 v146, v61, v16, vcc
	v_add_u32_e32 v16, 0xd600, v64
	v_cndmask_b32_e32 v147, v61, v16, vcc
	v_and_b32_e32 v16, -16, v52
	v_add_u32_e32 v65, 0xd400, v64
	v_cmp_ne_u32_e64 s[18:19], 16, v16
	v_lshl_add_u32 v16, v94, 6, 0
	v_lshlrev_b32_e32 v53, 5, v52
	s_mov_b32 s28, 0x9c00
	s_movk_i32 s29, 0xc0
	s_movk_i32 s30, 0xff90
	v_cndmask_b32_e32 v148, v61, v65, vcc
	v_add3_u32 v55, v16, v53, s28
	v_mad_u64_u32 v[60:61], s[20:21], v94, s29, v[16:17]
	v_mul_lo_u32 v16, v94, s30
	v_lshlrev_b32_e32 v59, 4, v52
	v_add3_u32 v59, v60, v16, v59
	v_and_b32_e32 v16, -16, v54
	v_cmp_ne_u32_e64 s[20:21], 16, v16
	v_lshl_add_u32 v16, v95, 6, 0
	v_add_u32_e32 v53, v60, v53
	v_lshlrev_b32_e32 v64, 5, v54
	v_mad_u64_u32 v[60:61], s[22:23], v95, s29, v[16:17]
	v_add3_u32 v65, v16, v64, s28
	v_mul_lo_u32 v16, v95, s30
	v_lshlrev_b32_e32 v61, 4, v54
	v_add3_u32 v71, v60, v16, v61
	v_and_b32_e32 v16, -16, v56
	v_cmp_ne_u32_e64 s[22:23], 16, v16
	v_lshl_add_u32 v16, v96, 6, 0
	v_add_u32_e32 v64, v60, v64
	v_lshlrev_b32_e32 v72, 5, v56
	v_mad_u64_u32 v[60:61], s[24:25], v96, s29, v[16:17]
	v_add3_u32 v82, v16, v72, s28
	v_mul_lo_u32 v16, v96, s30
	v_lshlrev_b32_e32 v61, 4, v56
	v_add3_u32 v158, v60, v16, v61
	v_and_b32_e32 v16, -16, v58
	v_cmp_ne_u32_e64 s[24:25], 16, v16
	v_lshl_add_u32 v16, v97, 6, 0
	v_add_u32_e32 v83, v60, v72
	v_lshlrev_b32_e32 v72, 5, v58
	v_mad_u64_u32 v[60:61], s[26:27], v97, s29, v[16:17]
	v_add3_u32 v152, v16, v72, s28
	v_mul_lo_u32 v16, v97, s30
	v_lshlrev_b32_e32 v61, 4, v58
	v_add3_u32 v159, v60, v16, v61
	v_lshl_add_u32 v16, v86, 6, 0
	v_add_u32_e32 v153, v60, v72
	v_lshlrev_b32_e32 v72, 5, v84
	v_mad_u64_u32 v[60:61], s[26:27], v86, s29, v[16:17]
	v_add3_u32 v155, v16, v72, s28
	v_add_u32_e32 v16, v60, v72
	v_mul_lo_u32 v61, v86, s30
	v_lshlrev_b32_e32 v72, 4, v84
	v_mov_b32_e32 v149, s40
	v_mov_b32_e32 v150, s41
	v_cmp_gt_u32_e64 s[26:27], 32, v52
	v_add3_u32 v160, v60, v61, v72
	v_mov_b32_e32 v80, s42
	v_mov_b32_e32 v81, s34
	v_cmp_gt_i32_e32 vcc, 8, v52
	v_cndmask_b32_e64 v61, v149, v150, s[26:27]
	v_mov_b32_e32 v151, s39
	v_cmp_gt_u32_e64 s[26:27], 24, v52
	v_cndmask_b32_e32 v60, v80, v81, vcc
	v_cmp_gt_i32_e64 s[28:29], 16, v52
	v_cndmask_b32_e64 v61, v61, v151, s[26:27]
	v_cmp_gt_u32_e64 s[30:31], 32, v54
	v_cndmask_b32_e64 v60, v61, v60, s[28:29]
	v_lshl_add_u32 v60, v52, 3, v60
	v_ashrrev_i32_e32 v61, 31, v60
	v_lshl_add_u64 v[72:73], v[60:61], 1, s[58:59]
	v_cmp_gt_i32_e64 s[28:29], 8, v54
	v_cndmask_b32_e64 v61, v149, v150, s[30:31]
	v_cmp_gt_u32_e64 s[30:31], 24, v54
	v_cndmask_b32_e64 v60, v80, v81, s[28:29]
	v_cmp_gt_i32_e64 s[34:35], 16, v54
	v_cndmask_b32_e64 v61, v61, v151, s[30:31]
	v_cmp_gt_u32_e64 s[36:37], 32, v56
	v_cndmask_b32_e64 v60, v61, v60, s[34:35]
	v_lshl_add_u32 v60, v54, 3, v60
	v_ashrrev_i32_e32 v61, 31, v60
	v_lshl_add_u64 v[74:75], v[60:61], 1, s[58:59]
	v_cmp_gt_i32_e64 s[34:35], 8, v56
	v_cndmask_b32_e64 v61, v149, v150, s[36:37]
	v_cmp_gt_u32_e64 s[36:37], 24, v56
	v_cndmask_b32_e64 v60, v80, v81, s[34:35]
	v_cmp_gt_i32_e64 s[38:39], 16, v56
	v_cndmask_b32_e64 v61, v61, v151, s[36:37]
	v_cmp_gt_u32_e64 s[40:41], 32, v58
	v_cndmask_b32_e64 v60, v61, v60, s[38:39]
	v_lshl_add_u32 v60, v56, 3, v60
	v_ashrrev_i32_e32 v61, 31, v60
	v_lshl_add_u64 v[76:77], v[60:61], 1, s[58:59]
	v_cmp_gt_i32_e64 s[38:39], 8, v58
	v_cndmask_b32_e64 v61, v149, v150, s[40:41]
	v_cmp_gt_u32_e64 s[40:41], 24, v58
	v_cndmask_b32_e64 v60, v80, v81, s[38:39]
	v_cmp_gt_i32_e64 s[42:43], 16, v58
	v_cndmask_b32_e64 v61, v61, v151, s[40:41]
	v_cmp_gt_u32_e64 s[44:45], 32, v84
	v_cndmask_b32_e64 v60, v61, v60, s[42:43]
	v_lshl_add_u32 v60, v58, 3, v60
	v_ashrrev_i32_e32 v61, 31, v60
	v_lshl_add_u64 v[78:79], v[60:61], 1, s[58:59]
	v_cmp_gt_i32_e64 s[42:43], 8, v84
	v_cndmask_b32_e64 v61, v149, v150, s[44:45]
	v_cmp_gt_u32_e64 s[44:45], 24, v84
	v_cndmask_b32_e64 v60, v80, v81, s[42:43]
	v_cmp_gt_i32_e64 s[48:49], 16, v84
	v_cndmask_b32_e64 v61, v61, v151, s[44:45]
	v_add_u32_e32 v57, 0x1f00, v53
	v_cndmask_b32_e64 v60, v61, v60, s[48:49]
	v_cmp_gt_u32_e64 s[48:49], 16, v52
	v_add_u32_e32 v70, 0x1f00, v64
	v_add_u32_e32 v85, 0x1f00, v83
	v_cndmask_b32_e64 v52, v55, v57, s[48:49]
	v_cndmask_b32_e32 v149, v52, v53, vcc
	v_cmp_gt_u32_e32 vcc, 16, v54
	v_add_u32_e32 v154, 0x1f00, v153
	v_add_u32_e32 v156, 0x1f00, v16
	v_cndmask_b32_e32 v53, v65, v70, vcc
	v_cmp_gt_u32_e32 vcc, 16, v56
	v_lshl_add_u32 v60, v84, 3, v60
	v_mov_b32_e32 v57, 0xc080
	v_cndmask_b32_e32 v54, v82, v85, vcc
	v_cmp_gt_u32_e32 vcc, 16, v58
	v_lshl_add_u32 v66, v90, 9, 0
	v_ashrrev_i32_e32 v61, 31, v60
	v_cndmask_b32_e32 v55, v152, v154, vcc
	v_cmp_gt_u32_e32 vcc, 16, v84
	v_cndmask_b32_e64 v52, v57, v254, s[26:27]
	v_cndmask_b32_e64 v150, v53, v64, s[28:29]
	v_cndmask_b32_e32 v56, v155, v156, vcc
	v_cndmask_b32_e64 v53, v57, v254, s[30:31]
	v_cndmask_b32_e64 v151, v54, v83, s[34:35]
	v_cndmask_b32_e64 v54, v57, v254, s[36:37]
	v_cndmask_b32_e64 v152, v55, v153, s[38:39]
	v_cndmask_b32_e64 v55, v57, v254, s[40:41]
	v_cndmask_b32_e64 v153, v56, v16, s[42:43]
	v_cndmask_b32_e64 v56, v57, v254, s[44:45]
	v_mov_b32_e32 v16, v17
	v_lshl_add_u32 v89, v87, 2, 0
	v_lshl_add_u64 v[80:81], v[60:61], 1, s[58:59]
	s_mov_b32 s34, -8
	v_add_u32_e32 v154, v62, v63
	v_add_u32_e32 v155, v66, v67
	v_add_u32_e32 v156, v59, v52
	v_add_u32_e32 v157, v71, v53
	v_add_u32_e32 v158, v158, v54
	v_add_u32_e32 v159, v159, v55
	v_add_u32_e32 v160, v160, v56
	v_add_u32_e32 v161, v68, v69
	v_mov_b64_e32 v[82:83], v[16:17]
	v_mov_b64_e32 v[84:85], v[16:17]
	v_mov_b32_e32 v52, v232
	v_mov_b32_e32 v53, v231
	v_mov_b32_e32 v54, v230
	v_mov_b32_e32 v55, v207
	s_waitcnt lgkmcnt(0)
	s_barrier
	v_mad_u64_u32 v[218:219], s[26:27], v94, s83, v[72:73]
	v_mad_u64_u32 v[220:221], s[26:27], v95, s83, v[74:75]
	v_mad_u64_u32 v[222:223], s[26:27], v96, s83, v[76:77]
	v_mad_u64_u32 v[244:245], s[26:27], v97, s83, v[78:79]
	v_mad_u64_u32 v[246:247], s[26:27], v86, s83, v[80:81]
	v_and_b32_e32 v98, 31, v119
	v_lshlrev_b32_e32 v98, 3, v98
	v_lshrrev_b32_e32 v99, 5, v119
	s_lshl_b32 s26, s32, 3
	v_add_u32_e32 v99, s26, v99
	v_lshl_add_u32 v99, v99, 2, v228
	v_add_u32_e32 v99, 0x6000, v99
	v_lshrrev_b32_e32 v100, 1, v119
	v_lshlrev_b32_e32 v100, 2, v100
	v_add_u32_e32 v100, 0xd400, v100
	v_lshrrev_b32_e32 v101, 3, v119
	v_lshlrev_b32_e32 v101, 9, v101
	v_and_b32_e32 v102, 7, v119
	v_lshl_add_u32 v101, v102, 6, v101
	v_add_u32_e32 v101, 0xd400, v101
	v_sub_u32_e32 v102, s26, v102
	v_lshlrev_b32_e32 v102, 1, v102
	v_ashrrev_i32_e32 v103, 31, v102
	v_lshl_add_u64 v[102:103], v[18:19], 0, v[102:103]
	s_load_dwordx2 s[26:27], s[84:85], 0x120
	v_lshrrev_b32_e32 v60, 3, v119
	v_and_b32_e32 v61, 7, v119
	v_mov_b32_e32 v62, s82
	v_add_u32_e32 v62, 0xffffff80, v62
	v_bfe_u32 v63, v62, 2, 3
	v_lshlrev_b32_e32 v63, 6, v63
	v_lshrrev_b32_e32 v64, 5, v62
	v_lshlrev_b32_e32 v64, 6, v64
	v_and_b32_e32 v65, 3, v62
	v_lshlrev_b32_e32 v65, 4, v65
	v_lshl_add_u32 v66, v61, 3, v63
	v_lshl_add_u32 v67, v61, 3, v64
	v_add_u32_e32 v67, 0x600, v67
	v_and_b32_e32 v68, 1, v119
	v_lshl_add_u32 v69, v68, 3, v63
	v_add_u32_e32 v69, v69, v65
	v_add_u32_e32 v69, 0x400, v69
	v_mul_u32_u24_e32 v70, 0x1200, v60
	v_lshrrev_b32_e32 v71, 1, v119
	v_mul_u32_u24_e32 v162, 0x1200, v71
	s_waitcnt lgkmcnt(0)
	s_add_u32 s26, s26, 0x6aa8000
	s_addc_u32 s27, s27, 0
	s_mov_b64 s[98:99], s[26:27]
	v_lshl_add_u32 v16, v66, 1, v70
	v_mov_b32_e32 v218, v16
	v_add_u32_e32 v16, 0x400, v16
	v_mov_b32_e32 v220, v16
	v_and_b32_e32 v62, 15, v119
	v_lshrrev_b32_e32 v63, 6, v119
	v_and_b32_e32 v65, 1, v63
	v_lshl_add_u32 v62, v65, 4, v62
	v_mul_u32_u24_e32 v62, 0x1200, v62
	v_lshrrev_b32_e32 v63, 1, v63
	v_lshlrev_b32_e32 v63, 7, v63
	v_bfe_u32 v65, v119, 4, 2
	v_lshl_add_u32 v63, v65, 3, v63
	v_add_u32_e32 v63, v63, v64
	v_add_u32_e32 v63, 0x600, v63
	v_lshl_add_u32 v16, v63, 1, v62
	v_mov_b32_e32 v222, v16
	v_add_u32_e32 v16, 64, v16
	v_mov_b32_e32 v244, v16
	v_lshl_add_u32 v16, v69, 1, v162
	v_mov_b32_e32 v246, v16
	v_lshlrev_b32_e32 v149, 8, v60
	v_lshl_add_u32 v149, v61, 5, v149
	v_add_u32_e32 v150, 0x2000, v149
	v_mul_u32_u24_e32 v156, 0x90, v60
	v_lshl_add_u32 v156, v61, 4, v156
	v_add_u32_e32 v156, 0xb000, v156
	v_add_u32_e32 v157, 0x1200, v156
	v_lshlrev_b32_e32 v151, 6, v71
	v_lshl_add_u32 v151, v68, 5, v151
	v_add_u32_e32 v151, 0xa000, v151
	v_mul_f32_e32 v117, s73, v117
	v_mul_f32_e32 v121, s73, v121
	v_mul_f32_e32 v123, s73, v123
	v_mul_f32_e32 v125, s73, v125
	v_add_u32_e32 v153, 0x100, v98
	v_add_u32_e32 v159, 0x400, v99
	v_add_u32_e32 v160, 0x800, v98
	v_add_u32_e32 v230, 0x1000, v98
	v_add_u32_e32 v231, 0x1800, v98
	v_add_u32_e32 v152, 0x8000, v161
	v_add_u32_e32 v158, 0x4000, v161
	v_and_b32_e32 v60, 15, v119
	v_mul_u32_u24_e32 v61, 12, v60
	v_add_u32_e32 v91, v91, v61
	v_add_u32_e32 v93, v93, v61
	v_readlane_b32 s26, v255, 18
	s_lshl_b32 s26, s26, 9
	v_mov_b32_e32 v62, s82
	v_add_u32_e32 v62, 0xffffff80, v62
	v_bfe_u32 v62, v62, 2, 3
	v_lshlrev_b32_e32 v62, 6, v62
	v_add_u32_e32 v62, s26, v62
	v_lshl_add_u32 v62, v60, 2, v62
	v_lshlrev_b32_e32 v16, 2, v62
	s_load_dwordx2 s[26:27], s[84:85], 0x78
	s_waitcnt lgkmcnt(0)
	global_load_dword v127, v16, s[26:27]
	global_load_dword v130, v16, s[26:27] offset:4
	global_load_dword v133, v16, s[26:27] offset:8
	global_load_dword v136, v16, s[26:27] offset:12
	s_load_dwordx2 s[26:27], s[84:85], 0x80
	s_waitcnt lgkmcnt(0)
	global_load_dword v128, v16, s[26:27]
	global_load_dword v131, v16, s[26:27] offset:4
	global_load_dword v134, v16, s[26:27] offset:8
	global_load_dword v137, v16, s[26:27] offset:12
	s_load_dwordx2 s[26:27], s[84:85], 0x88
	s_waitcnt lgkmcnt(0)
	global_load_dword v129, v16, s[26:27]
	global_load_dword v132, v16, s[26:27] offset:4
	global_load_dword v135, v16, s[26:27] offset:8
	global_load_dword v138, v16, s[26:27] offset:12
	s_waitcnt vmcnt(0)
	s_branch .LBB0_424

.LBB0_492:
	s_or_b64 exec, exec, s[26:27]
	s_waitcnt lgkmcnt(0)
	s_cmpk_lg_i32 s34, 0x1ff
	s_cselect_b64 s[28:29], -1, 0
	s_cmpk_eq_i32 s34, 0x1ff
	s_barrier
	s_cbranch_scc1 .LBB0_514
	s_add_i32 s26, s34, 9
	s_add_i32 s27, s34, 1
	s_cmp_lt_u32 s30, 7
	s_cselect_b32 s30, s26, s27
	s_cselect_b32 s26, 7, 0x1ff
	s_cselect_b32 s37, 0x100, s47
	s_cselect_b32 s36, 0x4000, 0
	s_sub_i32 s31, s26, s30
	s_and_b64 s[26:27], s[64:65], exec
	s_cselect_b32 s26, s30, s31
	s_lshl_b32 s38, s26, 5
	s_waitcnt vmcnt(3)
	s_add_i32 s26, s36, s38
	s_mul_i32 s26, s26, s83
	s_add_u32 s26, s98, s26
	s_addc_u32 s27, s99, 0
	global_load_dwordx4 v[20:23], v218, s[26:27]
	global_load_dwordx4 v[52:55], v220, s[26:27]
	global_load_dwordx4 v[28:31], v222, s[26:27]
	global_load_dwordx4 v[0:3], v244, s[26:27]
	s_and_saveexec_b64 s[30:31], s[14:15]
	s_cbranch_execz .Lri_skip4
	global_load_dwordx4 v[48:51], v246, s[26:27]
